# late-weight conversion moved from P5 sample-side WGs to WGs idle in the last GEMM round of P3
# baseline (speedup 1.0000x reference)
_Z4mega6Params:
	s_mov_b32 s98, 0
	s_load_dwordx8 s[24:31], s[0:1], 0xc0
	s_add_u32 s4, s0, 0xe0
	s_addc_u32 s5, s1, 0
	s_load_dword s34, s[0:1], 0xe0
	v_writelane_b32 v238, s4, 0
	s_nop 1
	v_writelane_b32 v238, s5, 1
	s_waitcnt lgkmcnt(0)
	s_add_u32 s4, s28, 0xf18d400
	s_addc_u32 s5, s29, 0
	v_writelane_b32 v238, s4, 2
	s_sub_i32 s3, s31, s30
	s_cmp_lt_i32 s3, 2
	v_writelane_b32 v238, s5, 3
	s_mov_b32 s3, 0
	v_writelane_b32 v238, s3, 4
	s_cbranch_scc1 .LBB0_17
	v_and_b32_e32 v1, 0x3ff, v0
	v_cmp_gt_u32_e32 vcc, 2, v1
	s_and_saveexec_b64 s[4:5], vcc
	v_lshl_add_u32 v2, v1, 2, 0
	v_add_u32_e32 v2, 0x23fc0, v2
	v_mov_b32_e32 v3, 0
	ds_write_b32 v2, v3
	s_or_b64 exec, exec, s[4:5]
	s_waitcnt lgkmcnt(0)
	s_barrier
	s_getreg_b32 s3, hwreg(HW_REG_XCC_ID, 0, 4)
	s_and_b32 s3, s3, 15
	v_cmp_eq_u32_e32 vcc, 0, v1
	v_writelane_b32 v238, s3, 4
	s_and_saveexec_b64 s[4:5], vcc
	s_cbranch_execz .LBB0_6
	s_mov_b64 s[6:7], exec
	v_mbcnt_lo_u32_b32 v2, s6, 0
	v_mbcnt_hi_u32_b32 v2, s7, v2
	v_cmp_eq_u32_e32 vcc, 0, v2
	s_and_b64 s[8:9], exec, vcc
	s_mov_b64 exec, s[8:9]
	s_cbranch_execz .LBB0_6
	v_readlane_b32 s3, v238, 4
	s_bcnt1_i32_b64 s6, s[6:7]
	s_lshl_b32 s3, s3, 8
	v_mov_b32_e32 v3, s6
	v_readlane_b32 s6, v238, 2
	v_mov_b32_e32 v2, s3
	v_readlane_b32 s7, v238, 3
	s_nop 4
	global_atomic_add v2, v3, s[6:7] offset:1024

.LBB0_1322:
	s_cmp_lg_u32 s98, 0
	s_cbranch_scc1 .Lcv_done
	s_mov_b32 s98, 2
	s_cmpk_lt_u32 s2, 0x81
	s_cbranch_scc1 .Lcv_done
	s_cmpk_lg_u32 s34, 0x100
	s_cbranch_scc1 .Lcv_done
	s_mov_b32 s98, 1
	s_waitcnt vmcnt(0) lgkmcnt(0)
	s_barrier
	s_mov_b32 s99, s34
	s_sub_u32 s52, s2, 0x81
	s_movk_i32 s34, 0xff
	v_and_b32_e32 v37, 0x3ff, v0
	s_branch .LBB0_2038

.LBB0_2038:
	s_cmp_eq_u32 s98, 1
	s_cbranch_scc1 .Lcv_go
	s_cmpk_eq_u32 s34, 0x100
	s_cbranch_scc1 .LBB0_2581

.LBB0_2581:
	s_cmp_lg_u32 s98, 1
	s_cbranch_scc1 .Lcv_n
	s_mov_b32 s98, 2
	s_mov_b32 s34, s99
	s_mov_b64 s[36:37], -1
	s_branch .Lcv_done

	.amdhsa_kernel _Z4mega6Params
		.amdhsa_group_segment_fixed_size 0
		.amdhsa_private_segment_fixed_size 0
		.amdhsa_kernarg_size 480
		.amdhsa_user_sgpr_count 2
		.amdhsa_user_sgpr_dispatch_ptr 0
		.amdhsa_user_sgpr_queue_ptr 0
		.amdhsa_user_sgpr_kernarg_segment_ptr 1
		.amdhsa_user_sgpr_dispatch_id 0
		.amdhsa_user_sgpr_kernarg_preload_length 0
		.amdhsa_user_sgpr_kernarg_preload_offset 0
		.amdhsa_user_sgpr_private_segment_size 0
		.amdhsa_uses_dynamic_stack 0
		.amdhsa_enable_private_segment 0
		.amdhsa_system_sgpr_workgroup_id_x 1
		.amdhsa_system_sgpr_workgroup_id_y 0
		.amdhsa_system_sgpr_workgroup_id_z 0
		.amdhsa_system_sgpr_workgroup_info 0
		.amdhsa_system_vgpr_workitem_id 2
		.amdhsa_next_free_vgpr 239
		.amdhsa_next_free_sgpr 100
		.amdhsa_accum_offset 240
		.amdhsa_reserve_vcc 1
		.amdhsa_float_round_mode_32 0
		.amdhsa_float_round_mode_16_64 0
		.amdhsa_float_denorm_mode_32 3
		.amdhsa_float_denorm_mode_16_64 3
		.amdhsa_dx10_clamp 1
		.amdhsa_ieee_mode 1
		.amdhsa_fp16_overflow 0
		.amdhsa_tg_split 0
		.amdhsa_exception_fp_ieee_invalid_op 0
		.amdhsa_exception_fp_denorm_src 0
		.amdhsa_exception_fp_ieee_div_zero 0
		.amdhsa_exception_fp_ieee_overflow 0
		.amdhsa_exception_fp_ieee_underflow 0
		.amdhsa_exception_fp_ieee_inexact 0
		.amdhsa_exception_int_div_zero 0
	.end_amdhsa_kernel

amdhsa.kernels:
  - .agpr_count:     0
    .args:
      - .offset:         0
        .size:           224
        .value_kind:     by_value
      - .offset:         224
        .size:           4
        .value_kind:     hidden_block_count_x
      - .offset:         228
        .size:           4
        .value_kind:     hidden_block_count_y
      - .offset:         232
        .size:           4
        .value_kind:     hidden_block_count_z
      - .offset:         236
        .size:           2
        .value_kind:     hidden_group_size_x
      - .offset:         238
        .size:           2
        .value_kind:     hidden_group_size_y
      - .offset:         240
        .size:           2
        .value_kind:     hidden_group_size_z
      - .offset:         242
        .size:           2
        .value_kind:     hidden_remainder_x
      - .offset:         244
        .size:           2
        .value_kind:     hidden_remainder_y
      - .offset:         246
        .size:           2
        .value_kind:     hidden_remainder_z
      - .offset:         264
        .size:           8
        .value_kind:     hidden_global_offset_x
      - .offset:         272
        .size:           8
        .value_kind:     hidden_global_offset_y
      - .offset:         280
        .size:           8
        .value_kind:     hidden_global_offset_z
      - .offset:         288
        .size:           2
        .value_kind:     hidden_grid_dims
      - .offset:         312
        .size:           8
        .value_kind:     hidden_multigrid_sync_arg
      - .offset:         344
        .size:           4
        .value_kind:     hidden_dynamic_lds_size
    .group_segment_fixed_size: 0
    .kernarg_segment_align: 8
    .kernarg_segment_size: 480
    .language:       OpenCL C
    .language_version:
      - 2
      - 0
    .max_flat_workgroup_size: 512
    .name:           _Z4mega6Params
    .private_segment_fixed_size: 0
    .sgpr_count:     106
    .sgpr_spill_count: 56
    .symbol:         _Z4mega6Params.kd
    .uniform_work_group_size: 1
    .uses_dynamic_stack: false
    .vgpr_count:     239
    .vgpr_spill_count: 0
    .wavefront_size: 64
